# FoX pair loop: next pair's LDS-DMA issue moved from right after the barrier to between the pair's two tiles
# speedup vs baseline: 1.0120x; 1.0074x over previous
; #define LAS3 __attribute__((address_space(3)))
; #define ATT_WAIT_BAR() asm volatile("s_waitcnt vmcnt(0) lgkmcnt(0)\n\ts_barrier" ::: "memory")
; __device__ __forceinline__ void fox_unit(int b, int hh, int qb, const bf16_t* Q, const bf16_t* __restrict__ K, const bf16_t* __restrict__ V, bf16_t* O, ...
;     ...
;         ATT_WAIT_BAR();
;         if (jp == NT / 2 - 1) { unsigned a = 0;
; #pragma unroll
;             for (int w = 0; w < 8; ++w) a |= flags[w];
;             excess = __builtin_amdgcn_readfirstlane(a) != 0u; }
;         const bool last = (jp == (excess ? 0 : jp_last0));
;         if (!last) { FOX_DMA(2 * jp - 1, (2 * jp - 1) & 3); FOX_DMA(2 * jp - 2, (2 * jp - 2) & 3); }
; #pragma unroll
;     ...
;         if (64 * jt <= qw0 + 31 && (excess || jp >= jp_lastw)) {
;             const LAS3 unsigned char* kp = kp0 + slot * SLOTB; const LAS3 unsigned char* fp = fp0 + slot * 1024;
;             asm volatile("" : "+v"(cinit));
;             f32x16 p0 = __builtin_amdgcn_mfma_f32_32x32x16_bf16(*(const LAS3 bf16x8*)(fp), qones, cinit, 0, 0, 0);
;             f32x16 p1 = __builtin_amdgcn_mfma_f32_32x32x16_bf16(*(const LAS3 bf16x8*)(fp + 512), qones, cinit, 0, 0, 0);
; #pragma unroll
;             for (int d0 = 0; d0 < 4; ++d0) {
;                 const bf16x8 k0 = *(const LAS3 bf16x8*)(kp + d0 * 2048), k1 = *(const LAS3 bf16x8*)(kp + d0 * 2048 + 512);
;                 p0 = __builtin_amdgcn_mfma_f32_32x32x16_bf16(k0, qr[d0], p0, 0, 0, 0);
;                 p1 = __builtin_amdgcn_mfma_f32_32x32x16_bf16(k1, qr[d0], p1, 0, 0, 0);
;             }
;             if (64 * jt + 63 > qw0) { const int kb_ = 64 * jt + 4 * hi - (qw0 + r32);
.LBB0_422:
	s_add_i32 s3, s88, s3
	s_or_b64 s[12:13], s[10:11], s[84:85]
	s_and_b64 s[12:13], s[12:13], exec
	s_cselect_b32 s7, 0, s75
	s_cmp_lg_u32 s3, s7
	s_cselect_b64 s[86:87], -1, 0
.LBB0_427:
	s_cmp_ge_i32 s3, s74
	s_cselect_b64 s[12:13], -1, 0
	s_or_b64 s[94:95], s[84:85], s[12:13]
	s_add_i32 s12, s96, s71
	s_add_i32 s7, s12, 0x1fc0
	s_cmp_le_u32 s7, s33
	s_cselect_b64 s[14:15], -1, 0
	s_and_b64 s[14:15], s[14:15], s[94:95]
	s_andn2_b64 vcc, exec, s[14:15]
	s_cbranch_vccnz .LBB0_431
	s_add_i32 s7, s6, -1
	s_and_b32 s7, s7, 3
	v_lshl_add_u32 v2, s7, 10, v166
	ds_read_b128 v[188:191], v2
	ds_read_b128 v[192:195], v2 offset:512
	s_lshl_b32 s7, s7, 13
	v_add_u32_e32 v2, s7, v137
	ds_read_b128 v[196:199], v2
	ds_read_b128 v[200:203], v2 offset:512
	ds_read_b128 v[204:207], v2 offset:2048
	ds_read_b128 v[208:211], v2 offset:2560
	ds_read_b128 v[212:215], v2 offset:4096
	ds_read_b128 v[216:219], v2 offset:4608
	ds_read_b128 v[220:223], v2 offset:6144
	ds_read_b128 v[224:227], v2 offset:6656
	s_addk_i32 s12, 0x1fff
	s_cmp_le_u32 s12, s70
	v_add_u32_e32 v186, s7, v165
	s_waitcnt lgkmcnt(9)
	v_mfma_f32_32x32x16_bf16 v[82:97], v[188:191], v[114:117], v[50:65]
	s_waitcnt lgkmcnt(8)
	v_mfma_f32_32x32x16_bf16 v[98:113], v[192:195], v[114:117], v[50:65]
	s_waitcnt lgkmcnt(7)
	v_mfma_f32_32x32x16_bf16 v[82:97], v[196:199], v[118:121], v[82:97]
	s_waitcnt lgkmcnt(6)
	v_mfma_f32_32x32x16_bf16 v[98:113], v[200:203], v[118:121], v[98:113]
	s_waitcnt lgkmcnt(5)
	v_mfma_f32_32x32x16_bf16 v[82:97], v[204:207], v[122:125], v[82:97]
	s_waitcnt lgkmcnt(4)
	v_mfma_f32_32x32x16_bf16 v[98:113], v[208:211], v[122:125], v[98:113]
	s_waitcnt lgkmcnt(3)
	v_mfma_f32_32x32x16_bf16 v[82:97], v[212:215], v[126:129], v[82:97]
	s_waitcnt lgkmcnt(2)
	v_mfma_f32_32x32x16_bf16 v[98:113], v[216:219], v[126:129], v[98:113]
	s_waitcnt lgkmcnt(1)
	v_mfma_f32_32x32x16_bf16 v[82:97], v[220:223], v[130:133], v[82:97]
	s_waitcnt lgkmcnt(0)
	v_mfma_f32_32x32x16_bf16 v[98:113], v[224:227], v[130:133], v[98:113]
	ds_read_b64_tr_b16 v[188:189], v186 offset:32768
	ds_read_b64_tr_b16 v[190:191], v186 offset:33280
	ds_read_b64_tr_b16 v[192:193], v186 offset:36864
	ds_read_b64_tr_b16 v[194:195], v186 offset:37376
	ds_read_b64_tr_b16 v[196:197], v186 offset:33792
	ds_read_b64_tr_b16 v[198:199], v186 offset:34304
	ds_read_b64_tr_b16 v[200:201], v186 offset:37888
	ds_read_b64_tr_b16 v[202:203], v186 offset:38400
	ds_read_b64_tr_b16 v[204:205], v186 offset:34816
	ds_read_b64_tr_b16 v[206:207], v186 offset:35328
	ds_read_b64_tr_b16 v[208:209], v186 offset:38912
	ds_read_b64_tr_b16 v[210:211], v186 offset:39424
	ds_read_b64_tr_b16 v[212:213], v186 offset:35840
	ds_read_b64_tr_b16 v[214:215], v186 offset:36352
	ds_read_b64_tr_b16 v[216:217], v186 offset:39936
	ds_read_b64_tr_b16 v[218:219], v186 offset:40448
	s_cbranch_scc1 .LBB0_430
; __device__ __forceinline__ void fox_unit(int b, int hh, int qb, const bf16_t* Q, const bf16_t* __restrict__ K, const bf16_t* __restrict__ V, bf16_t* O, ...
;     ...
;             if (64 * jt + 63 > qw0) { const int kb_ = 64 * jt + 4 * hi - (qw0 + r32);
; #pragma unroll
;                 for (int r = 0; r < 16; ++r) { const int cr = (r & 3) + 8 * (r >> 2); if (kb_ + cr > 0) p0[r] = -INFINITY; if (kb_ + cr + 32 > 0) p1[r] = -INFINITY; } }
	v_add_u32_e32 v2, s71, v155
	v_add_u32_e32 v2, 0xc0, v2
	s_movk_i32 s40, 0xffe6
	s_movk_i32 s68, 0xffe5
	s_movk_i32 s38, 0xffe7
	v_cmp_lt_i32_e64 s[66:67], s40, v2
	v_cmp_lt_i32_e64 s[68:69], s68, v2
	s_movk_i32 s36, 0xffe8
	v_cmp_lt_i32_e64 s[64:65], s38, v2
	s_and_b64 s[66:67], s[68:69], s[66:67]
	s_movk_i32 s34, 0xffed
	v_cmp_lt_i32_e64 s[62:63], s36, v2
	s_and_b64 s[64:65], s[66:67], s[64:65]
	s_movk_i32 s30, 0xffee
	v_cmp_lt_i32_e64 s[60:61], s34, v2
	s_and_b64 s[62:63], s[64:65], s[62:63]
	s_movk_i32 s28, 0xffef
	v_cmp_lt_i32_e64 s[58:59], s30, v2
	s_and_b64 s[60:61], s[62:63], s[60:61]
	v_cmp_lt_i32_e64 s[56:57], s28, v2
	s_and_b64 s[58:59], s[60:61], s[58:59]
	v_cmp_lt_i32_e64 s[54:55], -16, v2
	s_and_b64 s[56:57], s[58:59], s[56:57]
	v_cmp_lt_i32_e64 s[52:53], -11, v2
	s_and_b64 s[54:55], s[56:57], s[54:55]
	v_cmp_lt_i32_e64 s[50:51], -10, v2
	s_and_b64 s[52:53], s[54:55], s[52:53]
	v_cmp_lt_i32_e64 s[48:49], -9, v2
	s_and_b64 s[50:51], s[52:53], s[50:51]
	s_movk_i32 s14, 0xffe0
	v_cmp_lt_i32_e64 s[46:47], -8, v2
	s_and_b64 s[48:49], s[50:51], s[48:49]
	v_cmp_gt_i32_e64 s[12:13], 1, v2
	v_cmp_lt_i32_e32 vcc, s14, v2
	v_cmp_gt_i32_e64 s[14:15], 0, v2
	v_cmp_lt_i32_e64 s[44:45], -3, v2
	s_and_b64 s[46:47], s[48:49], s[46:47]
	s_or_b64 s[12:13], s[14:15], s[12:13]
	v_cmp_lt_i32_e64 s[42:43], -2, v2
	s_and_b64 s[44:45], s[46:47], s[44:45]
	v_cndmask_b32_e64 v4, v174, v83, s[14:15]
	v_cndmask_b32_e64 v5, v174, v82, s[12:13]
	s_and_b64 s[42:43], s[44:45], s[42:43]
	s_movk_i32 s40, 0xffc6
	v_cndmask_b32_e64 v82, v82, v5, s[42:43]
	v_cndmask_b32_e64 v84, v84, v174, s[42:43]
	v_cndmask_b32_e64 v83, v83, v4, s[42:43]
	s_movk_i32 s42, 0xffc5
	s_movk_i32 s38, 0xffc7
	v_cmp_lt_i32_e64 s[40:41], s40, v2
	v_cmp_lt_i32_e64 s[42:43], s42, v2
	s_movk_i32 s36, 0xffc8
	v_cmp_lt_i32_e64 s[38:39], s38, v2
	s_and_b64 s[40:41], s[42:43], s[40:41]
	s_movk_i32 s34, 0xffcd
	v_cmp_lt_i32_e64 s[36:37], s36, v2
	s_and_b64 s[38:39], s[40:41], s[38:39]
	s_movk_i32 s30, 0xffce
	v_cmp_lt_i32_e64 s[34:35], s34, v2
	s_and_b64 s[36:37], s[38:39], s[36:37]
	s_movk_i32 s28, 0xffcf
	v_cmp_lt_i32_e64 s[30:31], s30, v2
	s_and_b64 s[34:35], s[36:37], s[34:35]
	s_movk_i32 s26, 0xffd0
	v_cmp_lt_i32_e64 s[28:29], s28, v2
	s_and_b64 s[30:31], s[34:35], s[30:31]
	s_movk_i32 s24, 0xffd5
	v_cmp_lt_i32_e64 s[26:27], s26, v2
	s_and_b64 s[28:29], s[30:31], s[28:29]
	s_movk_i32 s22, 0xffd6
	v_cmp_lt_i32_e64 s[24:25], s24, v2
	s_and_b64 s[26:27], s[28:29], s[26:27]
	s_movk_i32 s20, 0xffd7
	v_cmp_lt_i32_e64 s[22:23], s22, v2
	s_and_b64 s[24:25], s[26:27], s[24:25]
	s_movk_i32 s18, 0xffd8
	v_cmp_lt_i32_e64 s[20:21], s20, v2
	s_and_b64 s[22:23], s[24:25], s[22:23]
	s_movk_i32 s16, 0xffdd
	v_cmp_lt_i32_e64 s[18:19], s18, v2
	s_and_b64 s[20:21], s[22:23], s[20:21]
	s_movk_i32 s14, 0xffde
	v_cmp_lt_i32_e64 s[16:17], s16, v2
	s_and_b64 s[18:19], s[20:21], s[18:19]
	s_movk_i32 s12, 0xffdf
	v_cmp_lt_i32_e64 s[14:15], s14, v2
	s_and_b64 s[16:17], s[18:19], s[16:17]
	v_cmp_lt_i32_e64 s[12:13], s12, v2
	s_and_b64 s[14:15], s[16:17], s[14:15]
	s_and_b64 s[12:13], s[14:15], s[12:13]
	s_and_b64 vcc, s[12:13], vcc
	v_cndmask_b32_e64 v97, v97, v174, s[68:69]
	v_cndmask_b32_e64 v96, v96, v174, s[66:67]
	v_cndmask_b32_e64 v95, v95, v174, s[64:65]
	v_cndmask_b32_e64 v94, v94, v174, s[62:63]
	v_cndmask_b32_e64 v93, v93, v174, s[60:61]
	v_cndmask_b32_e64 v92, v92, v174, s[58:59]
	v_cndmask_b32_e64 v91, v91, v174, s[56:57]
	v_cndmask_b32_e64 v90, v90, v174, s[54:55]
	v_cndmask_b32_e64 v89, v89, v174, s[52:53]
	v_cndmask_b32_e64 v88, v88, v174, s[50:51]
	v_cndmask_b32_e64 v87, v87, v174, s[48:49]
	v_cndmask_b32_e64 v86, v86, v174, s[46:47]
	v_cndmask_b32_e64 v85, v85, v174, s[44:45]
	v_cndmask_b32_e64 v113, v113, v174, s[42:43]
	v_cndmask_b32_e64 v112, v112, v174, s[40:41]
	v_cndmask_b32_e64 v111, v111, v174, s[38:39]
	v_cndmask_b32_e64 v110, v110, v174, s[36:37]
	v_cndmask_b32_e64 v109, v109, v174, s[34:35]
	v_cndmask_b32_e64 v108, v108, v174, s[30:31]
	v_cndmask_b32_e64 v107, v107, v174, s[28:29]
	v_cndmask_b32_e64 v106, v106, v174, s[26:27]
	v_cndmask_b32_e64 v105, v105, v174, s[24:25]
	v_cndmask_b32_e64 v104, v104, v174, s[22:23]
	v_cndmask_b32_e64 v103, v103, v174, s[20:21]
	v_cndmask_b32_e64 v102, v102, v174, s[18:19]
	v_cndmask_b32_e64 v101, v101, v174, s[16:17]
	v_cndmask_b32_e64 v100, v100, v174, s[14:15]
	v_cndmask_b32_e64 v99, v99, v174, s[12:13]
	v_cndmask_b32_e32 v98, v98, v174, vcc

; __device__ __forceinline__ void fox_unit(int b, int hh, int qb, const bf16_t* Q, const bf16_t* __restrict__ K, const bf16_t* __restrict__ V, bf16_t* O, ...
;     ...
;         if (!last) { FOX_DMA(2 * jp - 1, (2 * jp - 1) & 3); FOX_DMA(2 * jp - 2, (2 * jp - 2) & 3); }
.LBB0_431:
	s_and_b64 vcc, exec, s[86:87]
	s_cbranch_vccz .Lfox_dma_done
	s_add_i32 s12, s6, 1
	s_ashr_i32 s13, s12, 31
	s_and_b32 s7, s12, 3
	s_lshl_b64 s[14:15], s[12:13], 17
	s_lshl_b32 s16, s7, 13
	v_lshl_add_u64 v[4:5], v[156:157], 0, s[14:15]
	s_add_i32 s17, s16, s93
	s_mov_b32 s18, m0
	s_mov_b32 m0, s17
	s_nop 0
	global_load_lds_dwordx4 v[4:5], off
	s_mov_b32 m0, s18
	v_lshl_add_u64 v[4:5], v[158:159], 0, s[14:15]
	s_add_i32 s14, s16, s5
	s_mov_b32 s15, m0
	s_mov_b32 m0, s14
	s_nop 0
	global_load_lds_dwordx4 v[4:5], off
	s_mov_b32 m0, s15
	s_and_b64 vcc, exec, s[0:1]
	s_cbranch_vccnz .LBB0_425
	s_lshl_b32 s7, s7, 10
	s_lshl_b64 s[12:13], s[12:13], 10
	s_add_i32 s7, s7, 0
	v_lshl_add_u64 v[4:5], v[160:161], 0, s[12:13]
	s_add_i32 s7, s7, 0x10000
	s_mov_b32 s12, m0
	s_mov_b32 m0, s7
	s_nop 0
	global_load_lds_dwordx4 v[4:5], off
	s_mov_b32 m0, s12
.LBB0_425:
	s_ashr_i32 s7, s6, 31
	s_and_b32 s12, s6, 2
	s_lshl_b64 s[14:15], s[6:7], 17
	s_lshl_b32 s13, s12, 13
	v_lshl_add_u64 v[4:5], v[156:157], 0, s[14:15]
	s_add_i32 s16, s13, s93
	s_mov_b32 s17, m0
	s_mov_b32 m0, s16
	s_nop 0
	global_load_lds_dwordx4 v[4:5], off
	s_mov_b32 m0, s17
	v_lshl_add_u64 v[4:5], v[158:159], 0, s[14:15]
	s_add_i32 s13, s13, s5
	s_mov_b32 s14, m0
	s_mov_b32 m0, s13
	s_nop 0
	global_load_lds_dwordx4 v[4:5], off
	s_mov_b32 m0, s14
	s_and_b64 vcc, exec, s[0:1]
	s_cbranch_vccnz .Lfox_dma_done
	s_lshl_b64 s[14:15], s[6:7], 10
	s_lshl_b32 s7, s12, 10
	s_add_i32 s7, s7, 0
	v_lshl_add_u64 v[4:5], v[160:161], 0, s[14:15]
	s_add_i32 s7, s7, 0x10000
	s_mov_b32 s12, m0
	s_mov_b32 m0, s7
	s_nop 0
	global_load_lds_dwordx4 v[4:5], off
	s_mov_b32 m0, s12
; #define LAS3 __attribute__((address_space(3)))
; __device__ __forceinline__ void fox_unit(int b, int hh, int qb, const bf16_t* Q, const bf16_t* __restrict__ K, const bf16_t* __restrict__ V, bf16_t* O, ...
;     ...
;         if (64 * jt <= qw0 + 31 && (excess || jp >= jp_lastw)) {
;             const LAS3 unsigned char* kp = kp0 + slot * SLOTB; const LAS3 unsigned char* fp = fp0 + slot * 1024;
;             asm volatile("" : "+v"(cinit));
;             f32x16 p0 = __builtin_amdgcn_mfma_f32_32x32x16_bf16(*(const LAS3 bf16x8*)(fp), qones, cinit, 0, 0, 0);
;             f32x16 p1 = __builtin_amdgcn_mfma_f32_32x32x16_bf16(*(const LAS3 bf16x8*)(fp + 512), qones, cinit, 0, 0, 0);
; #pragma unroll
;             for (int d0 = 0; d0 < 4; ++d0) {
;                 const bf16x8 k0 = *(const LAS3 bf16x8*)(kp + d0 * 2048), k1 = *(const LAS3 bf16x8*)(kp + d0 * 2048 + 512);
;                 p0 = __builtin_amdgcn_mfma_f32_32x32x16_bf16(k0, qr[d0], p0, 0, 0, 0);
;                 p1 = __builtin_amdgcn_mfma_f32_32x32x16_bf16(k1, qr[d0], p1, 0, 0, 0);
;             }
;             if (64 * jt + 63 > qw0) { const int kb_ = 64 * jt + 4 * hi - (qw0 + r32);
; #pragma unroll
;                 for (int r = 0; r < 16; ++r) { const int cr = (r & 3) + 8 * (r >> 2); if (kb_ + cr > 0) p0[r] = -INFINITY; if (kb_ + cr + 32 > 0) p1[r] = -INFINITY; } }
.Lfox_dma_done:
	s_add_i32 s12, s2, s71
	s_add_i32 s7, s12, 0xffffff80
	s_cmp_le_u32 s7, s33
	s_cselect_b64 s[14:15], -1, 0
	s_and_b64 s[14:15], s[14:15], s[94:95]
	s_andn2_b64 vcc, exec, s[14:15]
	s_cbranch_vccnz .LBB0_435
	s_add_i32 s7, s6, 2
	s_and_b32 s7, s7, 2
	v_lshl_add_u32 v2, s7, 10, v166
	ds_read_b128 v[188:191], v2
	ds_read_b128 v[192:195], v2 offset:512
	s_lshl_b32 s7, s7, 13
	v_add_u32_e32 v2, s7, v137
	ds_read_b128 v[196:199], v2
	ds_read_b128 v[200:203], v2 offset:512
	ds_read_b128 v[204:207], v2 offset:2048
	ds_read_b128 v[208:211], v2 offset:2560
	ds_read_b128 v[212:215], v2 offset:4096
	ds_read_b128 v[216:219], v2 offset:4608
	ds_read_b128 v[220:223], v2 offset:6144
	ds_read_b128 v[224:227], v2 offset:6656
	s_addk_i32 s12, 0xffbf
	s_cmp_le_u32 s12, s70
	v_add_u32_e32 v186, s7, v165
	s_waitcnt lgkmcnt(9)
	v_mfma_f32_32x32x16_bf16 v[82:97], v[188:191], v[114:117], v[50:65]
	s_waitcnt lgkmcnt(8)
	v_mfma_f32_32x32x16_bf16 v[98:113], v[192:195], v[114:117], v[50:65]
	s_waitcnt lgkmcnt(7)
	v_mfma_f32_32x32x16_bf16 v[82:97], v[196:199], v[118:121], v[82:97]
	s_waitcnt lgkmcnt(6)
	v_mfma_f32_32x32x16_bf16 v[98:113], v[200:203], v[118:121], v[98:113]
	s_waitcnt lgkmcnt(5)
	v_mfma_f32_32x32x16_bf16 v[82:97], v[204:207], v[122:125], v[82:97]
	s_waitcnt lgkmcnt(4)
	v_mfma_f32_32x32x16_bf16 v[98:113], v[208:211], v[122:125], v[98:113]
	s_waitcnt lgkmcnt(3)
	v_mfma_f32_32x32x16_bf16 v[82:97], v[212:215], v[126:129], v[82:97]
	s_waitcnt lgkmcnt(2)
	v_mfma_f32_32x32x16_bf16 v[98:113], v[216:219], v[126:129], v[98:113]
	s_waitcnt lgkmcnt(1)
	v_mfma_f32_32x32x16_bf16 v[82:97], v[220:223], v[130:133], v[82:97]
	s_waitcnt lgkmcnt(0)
	v_mfma_f32_32x32x16_bf16 v[98:113], v[224:227], v[130:133], v[98:113]
	ds_read_b64_tr_b16 v[188:189], v186 offset:32768
	ds_read_b64_tr_b16 v[190:191], v186 offset:33280
	ds_read_b64_tr_b16 v[192:193], v186 offset:36864
	ds_read_b64_tr_b16 v[194:195], v186 offset:37376
	ds_read_b64_tr_b16 v[196:197], v186 offset:33792
	ds_read_b64_tr_b16 v[198:199], v186 offset:34304
	ds_read_b64_tr_b16 v[200:201], v186 offset:37888
	ds_read_b64_tr_b16 v[202:203], v186 offset:38400
	ds_read_b64_tr_b16 v[204:205], v186 offset:34816
	ds_read_b64_tr_b16 v[206:207], v186 offset:35328
	ds_read_b64_tr_b16 v[208:209], v186 offset:38912
	ds_read_b64_tr_b16 v[210:211], v186 offset:39424
	ds_read_b64_tr_b16 v[212:213], v186 offset:35840
	ds_read_b64_tr_b16 v[214:215], v186 offset:36352
	ds_read_b64_tr_b16 v[216:217], v186 offset:39936
	ds_read_b64_tr_b16 v[218:219], v186 offset:40448
	s_cbranch_scc1 .LBB0_434
	v_add_u32_e32 v2, s71, v153
	s_movk_i32 s40, 0xffe6
	s_movk_i32 s68, 0xffe5
	s_movk_i32 s38, 0xffe7
	v_cmp_lt_i32_e64 s[66:67], s40, v2
	v_cmp_lt_i32_e64 s[68:69], s68, v2
	s_movk_i32 s36, 0xffe8
	v_cmp_lt_i32_e64 s[64:65], s38, v2
	s_and_b64 s[66:67], s[68:69], s[66:67]
	s_movk_i32 s34, 0xffed
	v_cmp_lt_i32_e64 s[62:63], s36, v2
	s_and_b64 s[64:65], s[66:67], s[64:65]
	s_movk_i32 s30, 0xffee
	v_cmp_lt_i32_e64 s[60:61], s34, v2
	s_and_b64 s[62:63], s[64:65], s[62:63]
	s_movk_i32 s28, 0xffef
	v_cmp_lt_i32_e64 s[58:59], s30, v2
	s_and_b64 s[60:61], s[62:63], s[60:61]
	v_cmp_lt_i32_e64 s[56:57], s28, v2
	s_and_b64 s[58:59], s[60:61], s[58:59]
	v_cmp_lt_i32_e64 s[54:55], -16, v2
	s_and_b64 s[56:57], s[58:59], s[56:57]
	v_cmp_lt_i32_e64 s[52:53], -11, v2
	s_and_b64 s[54:55], s[56:57], s[54:55]
	v_cmp_lt_i32_e64 s[50:51], -10, v2
	s_and_b64 s[52:53], s[54:55], s[52:53]
	v_cmp_lt_i32_e64 s[48:49], -9, v2
	s_and_b64 s[50:51], s[52:53], s[50:51]
	s_movk_i32 s14, 0xffe0
	v_cmp_lt_i32_e64 s[46:47], -8, v2
	s_and_b64 s[48:49], s[50:51], s[48:49]
	v_cmp_gt_i32_e64 s[12:13], 1, v2
	v_cmp_lt_i32_e32 vcc, s14, v2
	v_cmp_gt_i32_e64 s[14:15], 0, v2
	v_cmp_lt_i32_e64 s[44:45], -3, v2
	s_and_b64 s[46:47], s[48:49], s[46:47]
	s_or_b64 s[12:13], s[14:15], s[12:13]
	v_cmp_lt_i32_e64 s[42:43], -2, v2
	s_and_b64 s[44:45], s[46:47], s[44:45]
	v_cndmask_b32_e64 v4, v174, v83, s[14:15]
	v_cndmask_b32_e64 v5, v174, v82, s[12:13]
	s_and_b64 s[42:43], s[44:45], s[42:43]
	s_movk_i32 s40, 0xffc6
	v_cndmask_b32_e64 v82, v82, v5, s[42:43]
	v_cndmask_b32_e64 v84, v84, v174, s[42:43]
	v_cndmask_b32_e64 v83, v83, v4, s[42:43]
	s_movk_i32 s42, 0xffc5
	s_movk_i32 s38, 0xffc7
	v_cmp_lt_i32_e64 s[40:41], s40, v2
	v_cmp_lt_i32_e64 s[42:43], s42, v2
	s_movk_i32 s36, 0xffc8
	v_cmp_lt_i32_e64 s[38:39], s38, v2
	s_and_b64 s[40:41], s[42:43], s[40:41]
	s_movk_i32 s34, 0xffcd
	v_cmp_lt_i32_e64 s[36:37], s36, v2
	s_and_b64 s[38:39], s[40:41], s[38:39]
	s_movk_i32 s30, 0xffce
	v_cmp_lt_i32_e64 s[34:35], s34, v2
	s_and_b64 s[36:37], s[38:39], s[36:37]
	s_movk_i32 s28, 0xffcf
	v_cmp_lt_i32_e64 s[30:31], s30, v2
	s_and_b64 s[34:35], s[36:37], s[34:35]
	s_movk_i32 s26, 0xffd0
	v_cmp_lt_i32_e64 s[28:29], s28, v2
	s_and_b64 s[30:31], s[34:35], s[30:31]
	s_movk_i32 s24, 0xffd5
	v_cmp_lt_i32_e64 s[26:27], s26, v2
	s_and_b64 s[28:29], s[30:31], s[28:29]
	s_movk_i32 s22, 0xffd6
	v_cmp_lt_i32_e64 s[24:25], s24, v2
	s_and_b64 s[26:27], s[28:29], s[26:27]
	s_movk_i32 s20, 0xffd7
	v_cmp_lt_i32_e64 s[22:23], s22, v2
	s_and_b64 s[24:25], s[26:27], s[24:25]
	s_movk_i32 s18, 0xffd8
	v_cmp_lt_i32_e64 s[20:21], s20, v2
	s_and_b64 s[22:23], s[24:25], s[22:23]
	s_movk_i32 s16, 0xffdd
	v_cmp_lt_i32_e64 s[18:19], s18, v2
	s_and_b64 s[20:21], s[22:23], s[20:21]
	s_movk_i32 s14, 0xffde
	v_cmp_lt_i32_e64 s[16:17], s16, v2
	s_and_b64 s[18:19], s[20:21], s[18:19]
	s_movk_i32 s12, 0xffdf
	v_cmp_lt_i32_e64 s[14:15], s14, v2
	s_and_b64 s[16:17], s[18:19], s[16:17]
	v_cmp_lt_i32_e64 s[12:13], s12, v2
	s_and_b64 s[14:15], s[16:17], s[14:15]
	s_and_b64 s[12:13], s[14:15], s[12:13]
	s_and_b64 vcc, s[12:13], vcc
	v_cndmask_b32_e64 v97, v97, v174, s[68:69]
	v_cndmask_b32_e64 v96, v96, v174, s[66:67]
	v_cndmask_b32_e64 v95, v95, v174, s[64:65]
	v_cndmask_b32_e64 v94, v94, v174, s[62:63]
	v_cndmask_b32_e64 v93, v93, v174, s[60:61]
	v_cndmask_b32_e64 v92, v92, v174, s[58:59]
	v_cndmask_b32_e64 v91, v91, v174, s[56:57]
	v_cndmask_b32_e64 v90, v90, v174, s[54:55]
	v_cndmask_b32_e64 v89, v89, v174, s[52:53]
	v_cndmask_b32_e64 v88, v88, v174, s[50:51]
	v_cndmask_b32_e64 v87, v87, v174, s[48:49]
	v_cndmask_b32_e64 v86, v86, v174, s[46:47]
	v_cndmask_b32_e64 v85, v85, v174, s[44:45]
	v_cndmask_b32_e64 v113, v113, v174, s[42:43]
	v_cndmask_b32_e64 v112, v112, v174, s[40:41]
	v_cndmask_b32_e64 v111, v111, v174, s[38:39]
	v_cndmask_b32_e64 v110, v110, v174, s[36:37]
	v_cndmask_b32_e64 v109, v109, v174, s[34:35]
	v_cndmask_b32_e64 v108, v108, v174, s[30:31]
	v_cndmask_b32_e64 v107, v107, v174, s[28:29]
	v_cndmask_b32_e64 v106, v106, v174, s[26:27]
	v_cndmask_b32_e64 v105, v105, v174, s[24:25]
	v_cndmask_b32_e64 v104, v104, v174, s[22:23]
	v_cndmask_b32_e64 v103, v103, v174, s[20:21]
	v_cndmask_b32_e64 v102, v102, v174, s[18:19]
	v_cndmask_b32_e64 v101, v101, v174, s[16:17]
	v_cndmask_b32_e64 v100, v100, v174, s[14:15]
	v_cndmask_b32_e64 v99, v99, v174, s[12:13]
	v_cndmask_b32_e32 v98, v98, v174, vcc
